# DF loop: next-tile LDS-DMA loads via SGPR base + 32-bit lane offset, issued between chain-1 MFMAs instead of a burst at the loop head
# speedup vs baseline: 1.0195x; 1.0081x over previous
; __device__ __forceinline__ int my_tid(int wave0) { int l; asm volatile("v_mbcnt_lo_u32_b32 %0, -1, 0\n\tv_mbcnt_hi_u32_b32 %0, -1, %0" : "=&v"(l)); return wave0 * 64 + l; }
; #define LAS __attribute__((address_space(3)))
; #define VMW() asm volatile("s_waitcnt vmcnt(0)" ::: "memory")
; __device__ __forceinline__ unsigned kfmt_goff(int b) { const int row = b >> 8, cp = (b & 255) >> 4, ch = cp ^ (row & 7); return (unsigned)(row * PITCH + ch * 8); }
; __device__ __forceinline__ int v_rd_base(int lane) { return ((lane & 3) << 3) | (((lane >> 2) & 3) << 6) | (((lane >> 4) & 1) << 5) | (((lane >> 5) & 1) << 8); }
; #define LAS __attribute__((address_space(3)))
; template <bool FIXED>
; __device__ __forceinline__ void df_unit(LAS char* lds, bf16_t* QKV, const float* gsub, float lam, float post, int b, int h, int qb, int wave0, float mfix2) {
;     int tid_o = my_tid(wave0); asm volatile("" : "+v"(tid_o)); const int tid = tid_o, wid = __builtin_amdgcn_readfirstlane(tid >> 6), lane = tid & 63, r32 = lane & 31, hi = lane >> 5;
;     const int mp = wid >> 2, wq = wid & 3;
;     const int P0 = qb * 128, qlo = P0 + wq * 32, qm = qlo + r32 - 4 * hi;
;     const unsigned kg0 = kfmt_goff(wid * 1024 + lane * 16), kg1 = kfmt_goff((wid + 8) * 1024 + lane * 16);
;     const unsigned vg0 = vfmt_goff(wid * 1024 + lane * 16), vg1 = vfmt_goff((wid + 8) * 1024 + lane * 16);
;     bf16_t* rowsq = QKV + (size_t)(b * SEQ + qlo) * PITCH + h * 256;
;     bf16x8 qr[8];
; #pragma unroll
;     for (int d0 = 0; d0 < 8; ++d0) qr[d0] = *reinterpret_cast<const bf16x8*>(rowsq + (size_t)r32 * PITCH + mp * 128 + d0 * 16 + hi * 8);
;     const bf16_t* Kg = QKV + (size_t)(b * SEQ) * PITCH + 2048 + h * 256;
;     const bf16_t* Vg = QKV + (size_t)(b * SEQ) * PITCH + 4096 + h * 256;
;     const int NT = 2 * qb + 2;
;     const unsigned vbase = (unsigned)(size_t)(lds) + (unsigned)v_rd_base(lane);
;     LAS float* wsf = (LAS float*)(lds + SCR_OFF) + wid * 64; LAS float* li_l = wsf; LAS float* al_l = wsf + 32;
;     ...
;     f32x16 o[8] = {}; float m_reg = -1e30f, l_reg = 0.f;
;     DF_STAGE(0, 0); VMW(); __syncthreads();
.LBB0_142:
	v_readlane_b32 s0, v253, 2
	v_mbcnt_lo_u32_b32 v0, -1, 0
	v_mbcnt_hi_u32_b32 v0, -1, v0
	v_readlane_b32 s8, v255, 48
	v_readlane_b32 s10, v255, 52
	v_add_u32_e32 v14, s0, v0
	v_readlane_b32 s11, v255, 53
	v_readfirstlane_b32 s16, v14
	s_ashr_i32 s0, s16, 6
	v_and_b32_e32 v204, 63, v14
	s_lshl_b32 s5, s0, 10
	v_lshlrev_b32_e32 v15, 4, v204
	v_or_b32_e32 v0, s5, v15
	v_ashrrev_i32_e32 v3, 8, v0
	s_and_b32 s27, s0, 3
	v_lshrrev_b32_e32 v0, 4, v0
	v_and_b32_e32 v2, 7, v3
	s_add_i32 s0, s5, 0x2000
	v_bitop3_b32 v6, v0, v2, 15 bitop3:0x6c
	v_or_b32_e32 v2, s0, v15
	v_ashrrev_i32_e32 v7, 8, v2
	v_lshrrev_b32_e32 v4, 4, v2
	v_and_b32_e32 v2, 7, v7
	v_bitop3_b32 v8, v4, v2, 15 bitop3:0x6c
	v_bfe_u32 v5, v14, 2, 3
	v_and_b32_e32 v2, 0xfffff0, v3
	s_mov_b32 s0, 0xfffff3
	v_lshrrev_b32_e32 v10, 1, v3
	v_lshrrev_b32_e32 v11, 1, v14
	v_bitop3_b32 v2, v2, s0, v5 bitop3:0xc8
	v_and_b32_e32 v10, 4, v10
	v_and_b32_e32 v11, 8, v11
	v_lshlrev_b32_e32 v16, 3, v204
	v_or3_b32 v2, v2, v11, v10
	v_and_b32_e32 v9, 24, v16
	v_mul_i32_i24_e32 v2, 0x1800, v2
	v_and_b32_e32 v0, 0x60, v0
	s_lshl_b32 s4, s27, 5
	v_or3_b32 v2, v2, v0, v9
	v_and_b32_e32 v0, 0xfffff0, v7
	s_or_b32 s15, s4, s12
	v_bitop3_b32 v0, v0, s0, v5 bitop3:0xc8
	v_lshrrev_b32_e32 v5, 1, v7
	v_readlane_b32 s0, v255, 40
	v_and_b32_e32 v5, 4, v5
	s_or_b32 s0, s15, s0
	v_and_b32_e32 v203, 31, v14
	s_ashr_i32 s26, s16, 8
	v_or3_b32 v0, v0, v11, v5
	s_mul_hi_i32 s1, s0, 0x3000
	s_mulk_i32 s0, 0x3000
	v_mul_i32_i24_e32 v10, 0x1800, v0
	s_add_u32 s8, s8, s0
	v_readlane_b32 s0, v255, 49
	v_mul_u32_u24_e32 v0, 0x1800, v203
	s_addc_u32 s9, s0, s1
	v_lshlrev_b32_e32 v0, 1, v0
	s_lshl_b32 s0, s26, 7
	v_bfe_u32 v202, v14, 5, 1
	v_and_b32_e32 v11, 0x60, v4
	v_lshl_add_u64 v[4:5], s[8:9], 0, v[0:1]
	s_ashr_i32 s1, s0, 31
	v_lshl_add_u64 v[4:5], s[0:1], 1, v[4:5]
	v_lshlrev_b32_e32 v0, 4, v202
	v_lshl_add_u64 v[4:5], v[4:5], 0, v[0:1]
	v_mul_i32_i24_e32 v3, 0x1800, v3
	global_load_dwordx4 v[162:165], v[4:5], off
	global_load_dwordx4 v[166:169], v[4:5], off offset:32
	global_load_dwordx4 v[170:173], v[4:5], off offset:64
	global_load_dwordx4 v[174:177], v[4:5], off offset:96
	global_load_dwordx4 v[178:181], v[4:5], off offset:128
	global_load_dwordx4 v[182:185], v[4:5], off offset:160
	global_load_dwordx4 v[186:189], v[4:5], off offset:192
	global_load_dwordx4 v[190:193], v[4:5], off offset:224
	v_lshl_or_b32 v4, v6, 3, v3
	v_mul_i32_i24_e32 v3, 0x1800, v7
	v_mov_b32_e32 v5, v1
	v_readlane_b32 s0, v255, 50
	v_lshl_or_b32 v6, v8, 3, v3
	v_lshlrev_b64 v[4:5], 1, v[4:5]
	v_readlane_b32 s1, v255, 51
	s_add_i32 s18, s5, 0
	v_mov_b32_e32 v7, v1
	v_or3_b32 v8, v10, v11, v9
	v_lshl_add_u64 v[10:11], s[0:1], 0, v[4:5]
	s_mov_b32 m0, s18
	v_lshlrev_b64 v[6:7], 1, v[6:7]
	global_load_lds_dwordx4 v[10:11], off
	v_lshl_add_u64 v[12:13], s[0:1], 0, v[6:7]
	s_add_i32 m0, s18, 0x2000
	s_mov_b64 s[0:1], 0x100
	global_load_lds_dwordx4 v[12:13], off
	v_lshl_add_u64 v[10:11], v[10:11], 0, s[0:1]
	s_add_i32 m0, s18, 0x4000
	v_mov_b32_e32 v3, v1
	global_load_lds_dwordx4 v[10:11], off
	v_lshl_add_u64 v[10:11], v[12:13], 0, s[0:1]
	s_add_i32 m0, s18, 0x6000
	v_lshlrev_b64 v[2:3], 1, v[2:3]
	v_mov_b32_e32 v9, v1
	global_load_lds_dwordx4 v[10:11], off
	v_lshl_add_u64 v[10:11], s[10:11], 0, v[2:3]
	s_add_i32 m0, s18, 0x8000
	v_lshlrev_b64 v[8:9], 1, v[8:9]
	global_load_lds_dwordx4 v[10:11], off
	v_lshl_add_u64 v[12:13], s[10:11], 0, v[8:9]
	s_add_i32 m0, s18, 0xa000
	v_lshl_add_u64 v[10:11], v[10:11], 0, s[0:1]
	global_load_lds_dwordx4 v[12:13], off
	s_add_i32 m0, s18, 0xc000
	v_lshlrev_b32_e32 v205, 2, v202
	global_load_lds_dwordx4 v[10:11], off
	v_lshl_add_u64 v[10:11], v[12:13], 0, s[0:1]
	s_add_i32 m0, s18, 0xe000
	v_lshlrev_b32_e32 v13, 8, v203
	global_load_lds_dwordx4 v[10:11], off
	v_and_b32_e32 v10, 0xc0, v15
	v_lshlrev_b32_e32 v11, 1, v14
	v_lshlrev_b32_e32 v15, 4, v14
	v_bitop3_b32 v14, v202, v14, 7 bitop3:0x78
	v_and_b32_e32 v15, 0x70, v15
	v_lshl_or_b32 v206, v14, 4, v13
	v_or_b32_e32 v14, 32, v0
	v_and_b32_e32 v12, 0x118, v16
	s_lshl_b32 s0, s26, 14
	v_bitop3_b32 v207, v14, v13, v15 bitop3:0xde
	v_or_b32_e32 v14, 64, v0
	v_or_b32_e32 v0, 0x60, v0
	s_add_i32 s34, s0, 0
	v_bitop3_b32 v209, v0, v13, v15 bitop3:0xde
	v_and_or_b32 v0, v11, 32, v12
	s_add_i32 s0, 0, 0x8000
	v_add3_u32 v214, v10, s0, v0
	s_add_i32 s0, s12, s4
	v_bitop3_b32 v208, v14, v13, v15 bitop3:0xde
	v_add_u32_e32 v0, s0, v203
	v_mov_b32_e32 v14, v1
	v_mov_b32_e32 v15, v1
	s_waitcnt vmcnt(0)
; #define LAS __attribute__((address_space(3)))
; #define VMW() asm volatile("s_waitcnt vmcnt(0)" ::: "memory")
; __device__ __forceinline__ int v_rd_base(int lane) { return ((lane & 3) << 3) | (((lane >> 2) & 3) << 6) | (((lane >> 4) & 1) << 5) | (((lane >> 5) & 1) << 8); }
; #define LAS __attribute__((address_space(3)))
; template <bool FIXED>
; __device__ __forceinline__ void df_unit(LAS char* lds, bf16_t* QKV, const float* gsub, float lam, float post, int b, int h, int qb, int wave0, float mfix2) {
;     ...
;     const int NT = 2 * qb + 2;
;     const unsigned vbase = (unsigned)(size_t)(lds) + (unsigned)v_rd_base(lane);
;     LAS float* wsf = (LAS float*)(lds + SCR_OFF) + wid * 64; LAS float* li_l = wsf; LAS float* al_l = wsf + 32;
;     ...
;     f32x16 o[8] = {}; float m_reg = -1e30f, l_reg = 0.f;
;     DF_STAGE(0, 0); VMW(); __syncthreads();
;     for (int t = 0; t < NT; ++t) {
	v_mov_b32_e32 v194, v4
	v_mov_b32_e32 v196, v6
	v_mov_b32_e32 v198, v2
	v_mov_b32_e32 v200, v8
	v_sub_u32_e32 v215, v0, v205
	v_mov_b32_e32 v0, v1
	v_mov_b32_e32 v2, v1
	v_mov_b32_e32 v3, v1
	v_mov_b32_e32 v4, v1
	v_mov_b32_e32 v5, v1
	v_mov_b32_e32 v6, v1
	v_mov_b32_e32 v7, v1
	v_mov_b32_e32 v8, v1
	v_mov_b32_e32 v9, v1
	v_mov_b32_e32 v10, v1
	v_mov_b32_e32 v11, v1
	v_mov_b32_e32 v12, v1
	v_mov_b32_e32 v13, v1
	v_mov_b64_e32 v[128:129], v[14:15]
	v_mov_b64_e32 v[112:113], v[14:15]
	v_mov_b64_e32 v[96:97], v[14:15]
	v_mov_b64_e32 v[80:81], v[14:15]
	v_mov_b64_e32 v[64:65], v[14:15]
	v_mov_b64_e32 v[48:49], v[14:15]
	v_mov_b64_e32 v[32:33], v[14:15]
	s_lshl_b32 s21, s98, 1
	v_mov_b64_e32 v[126:127], v[12:13]
	v_mov_b64_e32 v[124:125], v[10:11]
	v_mov_b64_e32 v[122:123], v[8:9]
	v_mov_b64_e32 v[120:121], v[6:7]
	v_mov_b64_e32 v[118:119], v[4:5]
	v_mov_b64_e32 v[116:117], v[2:3]
	v_mov_b64_e32 v[114:115], v[0:1]
	v_mov_b64_e32 v[110:111], v[12:13]
	v_mov_b64_e32 v[108:109], v[10:11]
	v_mov_b64_e32 v[106:107], v[8:9]
	v_mov_b64_e32 v[104:105], v[6:7]
	v_mov_b64_e32 v[102:103], v[4:5]
	v_mov_b64_e32 v[100:101], v[2:3]
	v_mov_b64_e32 v[98:99], v[0:1]
	v_mov_b64_e32 v[94:95], v[12:13]
	v_mov_b64_e32 v[92:93], v[10:11]
	v_mov_b64_e32 v[90:91], v[8:9]
	v_mov_b64_e32 v[88:89], v[6:7]
	v_mov_b64_e32 v[86:87], v[4:5]
	v_mov_b64_e32 v[84:85], v[2:3]
	v_mov_b64_e32 v[82:83], v[0:1]
	v_mov_b64_e32 v[78:79], v[12:13]
	v_mov_b64_e32 v[76:77], v[10:11]
	v_mov_b64_e32 v[74:75], v[8:9]
	v_mov_b64_e32 v[72:73], v[6:7]
	v_mov_b64_e32 v[70:71], v[4:5]
	v_mov_b64_e32 v[68:69], v[2:3]
	v_mov_b64_e32 v[66:67], v[0:1]
	v_mov_b64_e32 v[62:63], v[12:13]
	v_mov_b64_e32 v[60:61], v[10:11]
	v_mov_b64_e32 v[58:59], v[8:9]
	v_mov_b64_e32 v[56:57], v[6:7]
	v_mov_b64_e32 v[54:55], v[4:5]
	v_mov_b64_e32 v[52:53], v[2:3]
	v_mov_b64_e32 v[50:51], v[0:1]
	v_mov_b64_e32 v[46:47], v[12:13]
	v_mov_b64_e32 v[44:45], v[10:11]
	v_mov_b64_e32 v[42:43], v[8:9]
	v_mov_b64_e32 v[40:41], v[6:7]
	v_mov_b64_e32 v[38:39], v[4:5]
	v_mov_b64_e32 v[36:37], v[2:3]
	v_mov_b64_e32 v[34:35], v[0:1]
	v_mov_b64_e32 v[30:31], v[12:13]
	v_mov_b64_e32 v[28:29], v[10:11]
	v_mov_b64_e32 v[26:27], v[8:9]
	v_mov_b64_e32 v[24:25], v[6:7]
	v_mov_b64_e32 v[22:23], v[4:5]
	v_mov_b64_e32 v[20:21], v[2:3]
	v_mov_b64_e32 v[18:19], v[0:1]
	v_mov_b64_e32 v[16:17], v[14:15]
	s_mov_b32 s19, 63
	s_mov_b32 s20, 1
	s_add_i32 s21, s21, 2
	s_or_b32 s33, s15, 31
	s_add_u32 s35, s13, 0x180000
	v_mov_b32_e32 v216, 0
	s_mov_b64 s[10:11], 0
	v_mov_b64_e32 v[14:15], v[12:13]
	v_mov_b64_e32 v[12:13], v[10:11]
	v_mov_b64_e32 v[10:11], v[8:9]
	v_mov_b64_e32 v[8:9], v[6:7]
	v_mov_b64_e32 v[6:7], v[4:5]
	v_mov_b64_e32 v[4:5], v[2:3]
	v_mov_b64_e32 v[2:3], v[0:1]
	s_waitcnt vmcnt(0) lgkmcnt(0)
	s_barrier
	s_branch .LBB0_145

; #define SBAR() __builtin_amdgcn_sched_barrier(0)
; #define VMW() asm volatile("s_waitcnt vmcnt(0)" ::: "memory")
; #define KRD8(a, o_) do { KRD(a##0, kb0, (o_)); KRD(a##1, kb1, (o_)); KRD(a##2, kb2, (o_)); KRD(a##3, kb3, (o_)); KRD(a##4, kb0, (o_) + 128); KRD(a##5, kb1, (o_) + 128); KRD(a##6, kb2, (o_) + 128); KRD(a##7, kb3, (o_) + 128); } while (0)
; template <bool ALL16>
; __device__ __forceinline__ void qkt_b(f32x16& p0, f32x16& p1, unsigned kt, int r32, int hi, const bf16x8* qr) {
;     unsigned kb0 = kt + KSWZ(r32, (0 * 16 + hi * 8) * 2), kb1 = kt + KSWZ(r32, (1 * 16 + hi * 8) * 2), kb2 = kt + KSWZ(r32, (2 * 16 + hi * 8) * 2), kb3 = kt + KSWZ(r32, (3 * 16 + hi * 8) * 2);
;     ...
;     bf16x8 a0, a1, a2, a3, a4, a5, a6, a7;
;     p0 = f32x16{}; p1 = f32x16{};
;     if constexpr (ALL16) {
;         bf16x8 c0, c1, c2, c3, c4, c5, c6, c7;
;         KRD8(a, 0); KRD8(c, 8192);
;         asm volatile("s_waitcnt lgkmcnt(8)" ::: "memory"); SBAR();
;         KMMA8(p0, a);
; template <bool FIXED>
; __device__ __forceinline__ void df_unit(LAS char* lds, bf16_t* QKV, const float* gsub, float lam, float post, int b, int h, int qb, int wave0, float mfix2) {
;     ...
;     f32x16 o[8] = {}; float m_reg = -1e30f, l_reg = 0.f;
;     DF_STAGE(0, 0); VMW(); __syncthreads();
;     for (int t = 0; t < NT; ++t) {
;         const int bf = t & 1, kb = t * 64;
;         if (t + 1 < NT) DF_STAGE(t + 1, bf ^ 1);
.LBB0_145:
	s_add_i32 s0, s20, -1
	s_and_b32 s0, s0, 1
	s_sub_i32 s1, s19, 63
	s_cmp_gt_u32 s1, s33
	s_cbranch_scc1 .Ldf_inact
	s_cmp_ge_u32 s20, s21
	s_cbranch_scc1 .Ldf_qkB
	s_lshl_b32 s50, s0, 16
	s_xor_b32 s50, s50, 0x10000
	s_add_i32 s50, s18, s50
	s_add_u32 s40, s6, s10
	s_addc_u32 s41, s7, s11
	s_add_u32 s42, s40, s38
	s_addc_u32 s43, s41, s39
	s_add_u32 s44, s40, s22
	s_addc_u32 s45, s41, s23
	s_add_u32 s46, s40, s2
	s_addc_u32 s47, s41, s3
	s_add_u32 s48, s40, s24
	s_addc_u32 s49, s41, s25
	s_lshl_b32 s4, s0, 16
	s_add_i32 s0, s34, s4
	v_add_u32_e32 v0, s0, v206
	ds_read_b128 v[130:133], v0
	v_add_u32_e32 v217, s0, v207
	ds_read_b128 v[150:153], v217
	v_add_u32_e32 v233, s0, v208
	ds_read_b128 v[154:157], v233
	v_add_u32_e32 v246, s0, v209
	ds_read_b128 v[158:161], v246
	ds_read_b128 v[218:221], v0 offset:0x80
	ds_read_b128 v[234:237], v217 offset:0x80
	ds_read_b128 v[238:241], v233 offset:0x80
	ds_read_b128 v[242:245], v246 offset:0x80
	ds_read_b128 v[146:149], v0 offset:0x2000
	ds_read_b128 v[210:213], v217 offset:0x2000
	ds_read_b128 v[226:229], v233 offset:0x2000
	ds_read_b128 v[246:249], v246 offset:0x2000
	s_mov_b32 m0, s50
	s_nop 0
	global_load_lds_dwordx4 v194, s[42:43]
	s_add_i32 m0, s50, 0x2000
	s_nop 0
	global_load_lds_dwordx4 v196, s[42:43]
	s_waitcnt lgkmcnt(4)
	v_mfma_f32_32x32x16_bf16 v[130:145], v[130:133], v[162:165], 0
	s_add_i32 m0, s50, 0x4000
	s_nop 0
	global_load_lds_dwordx4 v194, s[44:45]
	v_mfma_f32_32x32x16_bf16 v[130:145], v[150:153], v[166:169], v[130:145]
	s_add_i32 m0, s50, 0x6000
	s_nop 0
	global_load_lds_dwordx4 v196, s[44:45]
	v_mfma_f32_32x32x16_bf16 v[130:145], v[154:157], v[170:173], v[130:145]
	s_add_i32 m0, s50, 0x8000
	s_nop 0
	global_load_lds_dwordx4 v198, s[46:47]
	v_mfma_f32_32x32x16_bf16 v[130:145], v[158:161], v[174:177], v[130:145]
	s_add_i32 m0, s50, 0xa000
	s_nop 0
	global_load_lds_dwordx4 v200, s[46:47]
	v_mfma_f32_32x32x16_bf16 v[130:145], v[218:221], v[178:181], v[130:145]
	ds_read_b128 v[218:221], v0 offset:0x2080
	v_add_u32_e32 v0, s0, v209
	s_add_i32 m0, s50, 0xc000
	s_nop 0
	global_load_lds_dwordx4 v198, s[48:49]
	v_mfma_f32_32x32x16_bf16 v[130:145], v[234:237], v[182:185], v[130:145]
	ds_read_b128 v[234:237], v217 offset:0x2080
	s_add_i32 m0, s50, 0xe000
	s_nop 0
	global_load_lds_dwordx4 v200, s[48:49]
	v_mfma_f32_32x32x16_bf16 v[130:145], v[238:241], v[186:189], v[130:145]
	ds_read_b128 v[238:241], v233 offset:0x2080
	v_mfma_f32_32x32x16_bf16 v[130:145], v[242:245], v[190:193], v[130:145]
	ds_read_b128 v[242:245], v0 offset:0x2080
	s_branch .Ldf_c2
.Ldf_qkB:
	s_lshl_b32 s4, s0, 16
	s_add_i32 s0, s34, s4
	v_add_u32_e32 v0, s0, v206
	ds_read_b128 v[130:133], v0
	v_add_u32_e32 v217, s0, v207
	ds_read_b128 v[150:153], v217
	v_add_u32_e32 v233, s0, v208
	ds_read_b128 v[154:157], v233
	v_add_u32_e32 v246, s0, v209
	ds_read_b128 v[158:161], v246
	ds_read_b128 v[218:221], v0 offset:0x80
	ds_read_b128 v[234:237], v217 offset:0x80
	ds_read_b128 v[238:241], v233 offset:0x80
	ds_read_b128 v[242:245], v246 offset:0x80
	ds_read_b128 v[146:149], v0 offset:0x2000
	ds_read_b128 v[210:213], v217 offset:0x2000
	ds_read_b128 v[226:229], v233 offset:0x2000
	ds_read_b128 v[246:249], v246 offset:0x2000
	s_waitcnt lgkmcnt(4)
	v_mfma_f32_32x32x16_bf16 v[130:145], v[130:133], v[162:165], 0
	v_mfma_f32_32x32x16_bf16 v[130:145], v[150:153], v[166:169], v[130:145]
	v_mfma_f32_32x32x16_bf16 v[130:145], v[154:157], v[170:173], v[130:145]
	v_mfma_f32_32x32x16_bf16 v[130:145], v[158:161], v[174:177], v[130:145]
	v_mfma_f32_32x32x16_bf16 v[130:145], v[218:221], v[178:181], v[130:145]
	ds_read_b128 v[218:221], v0 offset:0x2080
	v_add_u32_e32 v0, s0, v209
	v_mfma_f32_32x32x16_bf16 v[130:145], v[234:237], v[182:185], v[130:145]
	ds_read_b128 v[234:237], v217 offset:0x2080
	v_mfma_f32_32x32x16_bf16 v[130:145], v[238:241], v[186:189], v[130:145]
	ds_read_b128 v[238:241], v233 offset:0x2080
	v_mfma_f32_32x32x16_bf16 v[130:145], v[242:245], v[190:193], v[130:145]
	ds_read_b128 v[242:245], v0 offset:0x2080
; __device__ __forceinline__ int crow(int r, int hi) { return (r & 3) + 8 * (r >> 2) + 4 * hi; }
; __device__ __forceinline__ void finishSM(f32x16& p0, f32x16& p1, float alpha, float& l_reg, bf16x8& pa0, bf16x8& pa1, bf16x8& pa2, bf16x8& pa3) {
;     float ps = 0;
; #pragma unroll
;     for (int r = 0; r < 16; ++r) ps += p0[r];
; #pragma unroll
;     for (int r = 0; r < 16; ++r) ps += p1[r];
;     { auto rr = __builtin_amdgcn_permlane32_swap(__float_as_uint(ps), __float_as_uint(ps), false, false);
;       ps = __uint_as_float(rr[0]) + __uint_as_float(rr[1]); }
;     l_reg = l_reg * alpha + ps;
;     PK4(p0, 0, pa0); PK4(p0, 8, pa1); PK4(p1, 0, pa2); PK4(p1, 8, pa3);
; template <bool FIXED>
; __device__ __forceinline__ void df_unit(LAS char* lds, bf16_t* QKV, const float* gsub, float lam, float post, int b, int h, int qb, int wave0, float mfix2) {
;     ...
;             if constexpr (FIXED) { constexpr float C2f = LOG2E * SCALE; alpha = 1.f;
; #pragma unroll
;                 for (int r = 0; r < 16; ++r) { p0[r] = __builtin_amdgcn_exp2f(fmaf(p0[r], C2f, mfix2)); p1[r] = __builtin_amdgcn_exp2f(fmaf(p1[r], C2f, mfix2)); } }
;             else {
;             partialSM(p0, p1, m_reg, alpha);
;             if (__any(alpha < 1.f)) { if (hi == 0) al_l[r32] = alpha; asm volatile("s_waitcnt lgkmcnt(0)" ::: "memory");
; #pragma unroll
;                 for (int r = 0; r < 16; ++r) { const float a = al_l[crow(r, hi)];
; #pragma unroll
;                     for (int d = 0; d < 8; ++d) o[d][r] *= a; } }
;             }
;             finishSM(p0, p1, alpha, l_reg, pa0, pa1, pa2, pa3);
;             pv_tile2<8>(o, vbase + bf * 4 * TILE + 2 * TILE, pa0, pa1, pa2, pa3);
.Ldf_c2:
	s_cmp_le_u32 s19, s15
	s_cbranch_scc0 .Ldf_diag
	s_waitcnt lgkmcnt(4)
	v_mfma_f32_32x32x16_bf16 v[146:161], v[146:149], v[162:165], 0
	s_nop 3
	v_mfma_f32_32x32x16_bf16 v[146:161], v[210:213], v[166:169], v[146:161]
	s_nop 2
	v_fmamk_f32 v130, v130, 0x3e0293ee, v231
	v_fmamk_f32 v131, v131, 0x3e0293ee, v231
	v_exp_f32_e32 v130, v130
	v_exp_f32_e32 v131, v131
	v_mfma_f32_32x32x16_bf16 v[146:161], v[226:229], v[170:173], v[146:161]
	v_fmamk_f32 v132, v132, 0x3e0293ee, v231
	v_fmamk_f32 v133, v133, 0x3e0293ee, v231
	v_exp_f32_e32 v132, v132
	v_exp_f32_e32 v133, v133
	v_add_f32_e32 v217, 0, v130
	v_add_f32_e32 v217, v131, v217
	v_mfma_f32_32x32x16_bf16 v[146:161], v[246:249], v[174:177], v[146:161]
	v_fmamk_f32 v134, v134, 0x3e0293ee, v231
	v_fmamk_f32 v135, v135, 0x3e0293ee, v231
	v_exp_f32_e32 v134, v134
	v_exp_f32_e32 v135, v135
	v_add_f32_e32 v217, v132, v217
	v_add_f32_e32 v217, v133, v217
	s_waitcnt lgkmcnt(3)
	v_mfma_f32_32x32x16_bf16 v[146:161], v[218:221], v[178:181], v[146:161]
	v_fmamk_f32 v136, v136, 0x3e0293ee, v231
	v_fmamk_f32 v137, v137, 0x3e0293ee, v231
	v_exp_f32_e32 v136, v136
	v_exp_f32_e32 v137, v137
	v_add_f32_e32 v217, v134, v217
	v_add_f32_e32 v217, v135, v217
	s_waitcnt lgkmcnt(2)
	v_mfma_f32_32x32x16_bf16 v[146:161], v[234:237], v[182:185], v[146:161]
	v_fmamk_f32 v138, v138, 0x3e0293ee, v231
	v_fmamk_f32 v139, v139, 0x3e0293ee, v231
	v_exp_f32_e32 v138, v138
	v_exp_f32_e32 v139, v139
	v_add_f32_e32 v217, v136, v217
	v_add_f32_e32 v217, v137, v217
	s_waitcnt lgkmcnt(1)
	v_mfma_f32_32x32x16_bf16 v[146:161], v[238:241], v[186:189], v[146:161]
	v_fmamk_f32 v140, v140, 0x3e0293ee, v231
	v_fmamk_f32 v141, v141, 0x3e0293ee, v231
	v_exp_f32_e32 v140, v140
	v_exp_f32_e32 v141, v141
	v_add_f32_e32 v217, v138, v217
	v_add_f32_e32 v217, v139, v217
	s_waitcnt lgkmcnt(0)
	v_mfma_f32_32x32x16_bf16 v[146:161], v[242:245], v[190:193], v[146:161]
	v_fmamk_f32 v142, v142, 0x3e0293ee, v231
	v_fmamk_f32 v143, v143, 0x3e0293ee, v231
	v_exp_f32_e32 v142, v142
	v_exp_f32_e32 v143, v143
	v_add_f32_e32 v217, v140, v217
	v_add_f32_e32 v217, v141, v217
	v_fmamk_f32 v144, v144, 0x3e0293ee, v231
	v_fmamk_f32 v145, v145, 0x3e0293ee, v231
	v_exp_f32_e32 v144, v144
	v_exp_f32_e32 v145, v145
	v_add_f32_e32 v217, v142, v217
	v_add_f32_e32 v217, v143, v217
	v_add_f32_e32 v217, v144, v217
	v_add_f32_e32 v217, v145, v217
	v_cvt_pk_bf16_f32 v130, v130, v131
	v_cvt_pk_bf16_f32 v131, v132, v133
	v_cvt_pk_bf16_f32 v132, v134, v135
	v_cvt_pk_bf16_f32 v133, v136, v137
	v_cvt_pk_bf16_f32 v134, v138, v139
	v_cvt_pk_bf16_f32 v135, v140, v141
	v_cvt_pk_bf16_f32 v136, v142, v143
	v_cvt_pk_bf16_f32 v137, v144, v145
	v_permlane32_swap_b32_e32 v130, v132
	v_permlane32_swap_b32_e32 v131, v133
	v_permlane32_swap_b32_e32 v134, v136
	v_permlane32_swap_b32_e32 v135, v137
	v_fmamk_f32 v146, v146, 0x3e0293ee, v231
	v_fmamk_f32 v147, v147, 0x3e0293ee, v231
	v_exp_f32_e32 v146, v146
	v_exp_f32_e32 v147, v147
	v_fmamk_f32 v148, v148, 0x3e0293ee, v231
	v_fmamk_f32 v149, v149, 0x3e0293ee, v231
	v_exp_f32_e32 v148, v148
	v_exp_f32_e32 v149, v149
	v_add_f32_e32 v217, v146, v217
	v_add_f32_e32 v217, v147, v217
	v_fmamk_f32 v150, v150, 0x3e0293ee, v231
	v_fmamk_f32 v151, v151, 0x3e0293ee, v231
	v_exp_f32_e32 v150, v150
	v_exp_f32_e32 v151, v151
	v_add_f32_e32 v217, v148, v217
	v_add_f32_e32 v217, v149, v217
	v_fmamk_f32 v152, v152, 0x3e0293ee, v231
	v_fmamk_f32 v153, v153, 0x3e0293ee, v231
	v_exp_f32_e32 v152, v152
	v_exp_f32_e32 v153, v153
	v_add_f32_e32 v217, v150, v217
	v_add_f32_e32 v217, v151, v217
	v_fmamk_f32 v154, v154, 0x3e0293ee, v231
	v_fmamk_f32 v155, v155, 0x3e0293ee, v231
	v_exp_f32_e32 v154, v154
	v_exp_f32_e32 v155, v155
	v_add_f32_e32 v217, v152, v217
	v_add_f32_e32 v217, v153, v217
	v_fmamk_f32 v156, v156, 0x3e0293ee, v231
	v_fmamk_f32 v157, v157, 0x3e0293ee, v231
	v_exp_f32_e32 v156, v156
	v_exp_f32_e32 v157, v157
	v_add_f32_e32 v217, v154, v217
	v_add_f32_e32 v217, v155, v217
	v_fmamk_f32 v158, v158, 0x3e0293ee, v231
	v_fmamk_f32 v159, v159, 0x3e0293ee, v231
	v_exp_f32_e32 v158, v158
	v_exp_f32_e32 v159, v159
	v_add_f32_e32 v217, v156, v217
	v_add_f32_e32 v217, v157, v217
	v_fmamk_f32 v160, v160, 0x3e0293ee, v231
	v_fmamk_f32 v161, v161, 0x3e0293ee, v231
	v_exp_f32_e32 v160, v160
	v_exp_f32_e32 v161, v161
	v_add_f32_e32 v217, v158, v217
	v_add_f32_e32 v217, v159, v217
	s_nop 0
	v_add_f32_e32 v217, v160, v217
	v_add_f32_e32 v217, v161, v217
	v_cvt_pk_bf16_f32 v138, v146, v147
	v_cvt_pk_bf16_f32 v139, v148, v149
	v_cvt_pk_bf16_f32 v140, v150, v151
	v_cvt_pk_bf16_f32 v141, v152, v153
	v_cvt_pk_bf16_f32 v142, v154, v155
	v_cvt_pk_bf16_f32 v143, v156, v157
	v_cvt_pk_bf16_f32 v144, v158, v159
	v_cvt_pk_bf16_f32 v145, v160, v161
	s_nop 0
	v_permlane32_swap_b32_e32 v138, v140
	v_permlane32_swap_b32_e32 v139, v141
	v_permlane32_swap_b32_e32 v142, v144
	v_permlane32_swap_b32_e32 v143, v145
	s_branch .Ldf_pv

; #define VMW() asm volatile("s_waitcnt vmcnt(0)" ::: "memory")
; template <bool FIXED>
; __device__ __forceinline__ void df_unit(LAS char* lds, bf16_t* QKV, const float* gsub, float lam, float post, int b, int h, int qb, int wave0, float mfix2) {
;     ...
;     f32x16 o[8] = {}; float m_reg = -1e30f, l_reg = 0.f;
;     DF_STAGE(0, 0); VMW(); __syncthreads();
;     for (int t = 0; t < NT; ++t) {
;         const int bf = t & 1, kb = t * 64;
;         if (t + 1 < NT) DF_STAGE(t + 1, bf ^ 1);
;         if (kb <= qlo + 31) {
.Ldf_inact:
	s_cmp_ge_u32 s20, s21
	s_cbranch_scc1 .LBB0_144
	s_lshl_b32 s50, s0, 16
	s_xor_b32 s50, s50, 0x10000
	s_add_i32 s50, s18, s50
	s_add_u32 s40, s6, s10
	s_addc_u32 s41, s7, s11
	s_add_u32 s42, s40, s38
	s_addc_u32 s43, s41, s39
	s_add_u32 s44, s40, s22
	s_addc_u32 s45, s41, s23
	s_add_u32 s46, s40, s2
	s_addc_u32 s47, s41, s3
	s_add_u32 s48, s40, s24
	s_addc_u32 s49, s41, s25
	s_mov_b32 m0, s50
	s_nop 0
	global_load_lds_dwordx4 v194, s[42:43]
	s_add_i32 m0, s50, 0x2000
	s_nop 0
	global_load_lds_dwordx4 v196, s[42:43]
	s_add_i32 m0, s50, 0x4000
	s_nop 0
	global_load_lds_dwordx4 v194, s[44:45]
	s_add_i32 m0, s50, 0x6000
	s_nop 0
	global_load_lds_dwordx4 v196, s[44:45]
	s_add_i32 m0, s50, 0x8000
	s_nop 0
	global_load_lds_dwordx4 v198, s[46:47]
	s_add_i32 m0, s50, 0xa000
	s_nop 0
	global_load_lds_dwordx4 v200, s[46:47]
	s_add_i32 m0, s50, 0xc000
	s_nop 0
	global_load_lds_dwordx4 v198, s[48:49]
	s_add_i32 m0, s50, 0xe000
	s_nop 0
	global_load_lds_dwordx4 v200, s[48:49]
	s_branch .LBB0_144
